# final rmsnorm: loop-invariant gain vectors loaded once outside the row loop, no store-ack waits between stores
# speedup vs baseline: 1.0181x; 1.0013x over previous
.LBB0_19:
	s_andn2_b64 vcc, exec, s[12:13]
	s_cbranch_vccnz .LBB0_4
	v_readlane_b32 s4, v255, 24
	s_cmp_lg_u32 s4, 0
	s_cselect_b64 s[2:3], -1, 0
	v_readlane_b32 s5, v255, 25
	v_writelane_b32 v255, s2, 39
	s_and_b64 vcc, exec, s[2:3]
	s_nop 0
	v_writelane_b32 v255, s3, 40
	s_cbranch_vccz .LBB0_38
	s_xor_b64 s[4:5], s[10:11], -1
	s_mov_b64 s[10:11], -1
	s_and_b64 vcc, exec, s[4:5]
	s_cbranch_vccz .LBB0_676
	v_readlane_b32 s4, v255, 24
	s_cmp_lt_i32 s4, 17
	v_readlane_b32 s5, v255, 25
	s_cbranch_scc1 .LBB0_236
	v_readlane_b32 s4, v255, 24
	s_cmp_lt_i32 s4, 19
	v_readlane_b32 s5, v255, 25
	s_cbranch_scc1 .LBB0_71
	v_readlane_b32 s4, v255, 24
	s_cmp_lt_i32 s4, 20
	v_readlane_b32 s5, v255, 25
	s_cbranch_scc1 .LBB0_68
	v_readlane_b32 s4, v255, 24
	s_cmp_lt_i32 s4, 24
	v_readlane_b32 s5, v255, 25
	s_cbranch_scc1 .LBB0_32
	v_readlane_b32 s4, v255, 24
	s_cmp_eq_u32 s4, 24
	v_readlane_b32 s5, v255, 25
	s_cbranch_scc0 .LBB0_31
	v_mov_b32_e32 v1, v214
	v_readlane_b32 s4, v252, 7
	s_waitcnt vmcnt(0)
	v_ashrrev_i32_e32 v2, 6, v1
	s_movk_i32 s2, 0x4000
	v_add_u32_e32 v38, s4, v2
	v_mov_b32_e32 v1, v214
	v_cmp_gt_i32_e32 vcc, s2, v38
	s_and_saveexec_b64 s[10:11], vcc
	v_readlane_b32 s16, v254, 46
	v_readlane_b32 s14, v252, 8
	v_readlane_b32 s17, v254, 47
	s_movk_i32 s2, 0x3fff
	v_readlane_b32 s18, v254, 48
	v_readlane_b32 s19, v254, 49
	s_cbranch_execz .LBB0_30
	v_and_b32_e32 v2, 63, v1
	v_xor_b32_e32 v1, 32, v217
	v_cmp_lt_i32_e32 vcc, v1, v219
	v_xor_b32_e32 v3, 16, v217
	v_readlane_b32 s36, v255, 8
	v_cndmask_b32_e32 v1, v217, v1, vcc
	v_cmp_lt_i32_e32 vcc, v3, v219
	s_waitcnt lgkmcnt(1)
	v_lshlrev_b32_e32 v4, 4, v2
	s_waitcnt lgkmcnt(0)
	v_mov_b32_e32 v5, v0
	v_cndmask_b32_e32 v3, v217, v3, vcc
	v_lshlrev_b32_e32 v80, 2, v3
	v_xor_b32_e32 v3, 8, v217
	v_cmp_lt_i32_e32 vcc, v3, v219
	v_readlane_b32 s50, v255, 22
	v_readlane_b32 s51, v255, 23
	v_cndmask_b32_e32 v3, v217, v3, vcc
	v_lshlrev_b32_e32 v81, 2, v3
	v_xor_b32_e32 v3, 4, v217
	v_cmp_lt_i32_e32 vcc, v3, v219
	v_lshl_add_u64 v[40:41], s[50:51], 0, v[4:5]
	v_or_b32_e32 v4, 0x100, v2
	v_cndmask_b32_e32 v3, v217, v3, vcc
	v_lshlrev_b32_e32 v82, 2, v3
	v_xor_b32_e32 v3, 2, v217
	v_cmp_lt_i32_e32 vcc, v3, v219
	v_or_b32_e32 v6, 0x140, v2
	v_lshlrev_b32_e32 v12, 4, v4
	v_cndmask_b32_e32 v3, v217, v3, vcc
	v_mov_b32_e32 v13, v0
	v_lshlrev_b32_e32 v83, 2, v3
	v_xor_b32_e32 v3, 1, v217
	v_or_b32_e32 v8, 0x180, v2
	v_lshl_add_u64 v[42:43], s[50:51], 0, v[12:13]
	v_lshlrev_b32_e32 v12, 4, v6
	v_cmp_lt_i32_e32 vcc, v3, v219
	v_or_b32_e32 v10, 0x1c0, v2
	v_lshl_add_u64 v[44:45], s[50:51], 0, v[12:13]
	v_lshlrev_b32_e32 v12, 4, v8
	v_cndmask_b32_e32 v3, v217, v3, vcc
	v_lshl_add_u64 v[46:47], s[50:51], 0, v[12:13]
	v_lshlrev_b32_e32 v12, 4, v10
	v_lshlrev_b32_e32 v1, 2, v1
	v_lshlrev_b32_e32 v84, 2, v3
	v_lshl_add_u64 v[48:49], s[50:51], 0, v[12:13]
	s_mov_b64 s[12:13], 0
	v_lshlrev_b32_e32 v50, 4, v2
	v_mov_b32_e32 v51, v0
	v_lshlrev_b32_e32 v52, 4, v4
	v_mov_b32_e32 v53, v0
	v_lshlrev_b32_e32 v54, 4, v6
	v_mov_b32_e32 v55, v0
	v_lshlrev_b32_e32 v56, 4, v8
	v_mov_b32_e32 v57, v0
	v_lshlrev_b32_e32 v58, 4, v10
	v_mov_b32_e32 v59, v0
	v_readlane_b32 s37, v255, 9
	v_readlane_b32 s38, v255, 10
	v_readlane_b32 s39, v255, 11
	v_readlane_b32 s40, v255, 12
	v_readlane_b32 s41, v255, 13
	v_readlane_b32 s42, v255, 14
	v_readlane_b32 s43, v255, 15
	v_readlane_b32 s44, v255, 16
	v_readlane_b32 s45, v255, 17
	v_readlane_b32 s46, v255, 18
	v_readlane_b32 s47, v255, 19
	v_readlane_b32 s48, v255, 20
	v_readlane_b32 s49, v255, 21
	global_load_dwordx4 v[100:103], v[40:41], off
	global_load_dwordx4 v[104:107], v[40:41], off offset:1024
	global_load_dwordx4 v[108:111], v[40:41], off offset:2048
	global_load_dwordx4 v[112:115], v[40:41], off offset:3072
	global_load_dwordx4 v[116:119], v[42:43], off
	global_load_dwordx4 v[120:123], v[44:45], off
	global_load_dwordx4 v[124:127], v[46:47], off
	global_load_dwordx4 v[128:131], v[48:49], off
.LBB0_29:
	v_ashrrev_i32_e32 v39, 31, v38
	v_lshlrev_b64 v[2:3], 13, v[38:39]
	v_lshl_add_u64 v[2:3], s[16:17], 0, v[2:3]
	v_lshl_add_u64 v[68:69], v[2:3], 0, v[50:51]
	v_lshl_add_u64 v[66:67], v[2:3], 0, v[52:53]
	v_lshl_add_u64 v[64:65], v[2:3], 0, v[54:55]
	v_lshl_add_u64 v[62:63], v[2:3], 0, v[56:57]
	v_lshl_add_u64 v[60:61], v[2:3], 0, v[58:59]
	global_load_dwordx4 v[22:25], v[68:69], off
	global_load_dwordx4 v[26:29], v[68:69], off offset:1024
	global_load_dwordx4 v[14:17], v[68:69], off offset:2048
	global_load_dwordx4 v[10:13], v[68:69], off offset:3072
	global_load_dwordx4 v[6:9], v[66:67], off
	global_load_dwordx4 v[2:5], v[64:65], off
	v_add_u32_e32 v38, s14, v38
	s_waitcnt vmcnt(5)
	v_pk_mul_f32 v[74:75], v[22:23], v[22:23]
	s_waitcnt vmcnt(4)
	v_pk_mul_f32 v[86:87], v[26:27], v[26:27]
	v_pk_mul_f32 v[76:77], v[24:25], v[24:25]
	v_pk_mul_f32 v[88:89], v[28:29], v[28:29]
	s_waitcnt vmcnt(1)
	v_mov_b32_e32 v32, v7
	s_waitcnt vmcnt(0)
	v_mov_b32_e32 v33, v3
	v_mov_b32_e32 v30, v6
	v_mov_b32_e32 v31, v2
	v_pk_mul_f32 v[32:33], v[32:33], v[32:33]
	v_mov_b32_e32 v34, v9
	v_pk_fma_f32 v[30:31], v[30:31], v[30:31], v[32:33]
	v_mov_b32_e32 v32, v8
	v_mov_b32_e32 v33, v4
	v_mov_b32_e32 v35, v5
	v_pk_fma_f32 v[30:31], v[32:33], v[32:33], v[30:31]
	v_add_f32_e32 v39, v86, v87
	v_pk_fma_f32 v[72:73], v[34:35], v[34:35], v[30:31]
	global_load_dwordx4 v[34:37], v[62:63], off
	global_load_dwordx4 v[30:33], v[60:61], off
	v_add_f32_e32 v74, v74, v75
	v_add_f32_e32 v39, v39, v88
	v_add_f32_e32 v74, v74, v76
	v_pk_mul_f32 v[90:91], v[14:15], v[14:15]
	v_add_f32_e32 v39, v39, v89
	v_add_f32_e32 v74, v74, v77
	v_pk_mul_f32 v[78:79], v[16:17], v[16:17]
	v_add_f32_e32 v39, v74, v39
	v_add_f32_e32 v74, v90, v91
	v_add_f32_e32 v74, v74, v78
	v_pk_mul_f32 v[92:93], v[10:11], v[10:11]
	v_add_f32_e32 v74, v74, v79
	v_pk_mul_f32 v[70:71], v[12:13], v[12:13]
	v_add_f32_e32 v39, v39, v74
	v_add_f32_e32 v74, v92, v93
	v_add_f32_e32 v70, v74, v70
	v_add_f32_e32 v70, v70, v71
	v_add_f32_e32 v39, v39, v70
	v_add_f32_e32 v39, v39, v72
	v_add_f32_e32 v39, v39, v73
	s_waitcnt vmcnt(1)
	v_mov_b32_e32 v96, v35
	s_waitcnt vmcnt(0)
	v_mov_b32_e32 v97, v31
	v_mov_b32_e32 v94, v34
	v_mov_b32_e32 v95, v30
	v_pk_mul_f32 v[96:97], v[96:97], v[96:97]
	v_mov_b32_e32 v98, v37
	v_pk_fma_f32 v[94:95], v[94:95], v[94:95], v[96:97]
	v_mov_b32_e32 v96, v36
	v_mov_b32_e32 v97, v32
	v_mov_b32_e32 v99, v33
	v_pk_fma_f32 v[94:95], v[96:97], v[96:97], v[94:95]
	s_nop 0
	v_pk_fma_f32 v[94:95], v[98:99], v[98:99], v[94:95]
	s_nop 0
	v_add_f32_e32 v39, v39, v94
	v_add_f32_e32 v39, v39, v95
	ds_bpermute_b32 v70, v1, v39
	s_waitcnt lgkmcnt(0)
	v_add_f32_e32 v39, v39, v70
	ds_bpermute_b32 v70, v80, v39
	s_waitcnt lgkmcnt(0)
	v_add_f32_e32 v39, v39, v70
	ds_bpermute_b32 v70, v81, v39
	s_waitcnt lgkmcnt(0)
	v_add_f32_e32 v39, v39, v70
	ds_bpermute_b32 v70, v82, v39
	s_waitcnt lgkmcnt(0)
	v_add_f32_e32 v39, v39, v70
	ds_bpermute_b32 v70, v83, v39
	s_waitcnt lgkmcnt(0)
	v_add_f32_e32 v39, v39, v70
	ds_bpermute_b32 v70, v84, v39
	s_waitcnt lgkmcnt(0)
	v_add_f32_e32 v39, v39, v70
	v_fmamk_f32 v39, v39, 0x3a000000, v215
	v_cmp_gt_f32_e32 vcc, s65, v39
	v_mul_f32_e32 v70, 0x4b800000, v39
	s_nop 0
	v_cndmask_b32_e32 v39, v39, v70, vcc
	v_rsq_f32_e32 v39, v39
	s_nop 0
	v_mul_f32_e32 v70, 0x45800000, v39
	v_cndmask_b32_e32 v70, v39, v70, vcc
	v_pk_mul_f32 v[22:23], v[22:23], v[70:71] op_sel_hi:[1,0]
	v_pk_mul_f32 v[14:15], v[14:15], v[70:71] op_sel_hi:[1,0]
	v_pk_mul_f32 v[18:19], v[100:101], v[22:23]
	v_pk_mul_f32 v[22:23], v[24:25], v[70:71] op_sel_hi:[1,0]
	v_pk_mul_f32 v[16:17], v[16:17], v[70:71] op_sel_hi:[1,0]
	v_pk_mul_f32 v[20:21], v[102:103], v[22:23]
	global_store_dwordx4 v[68:69], v[18:21], off
	v_pk_mul_f32 v[22:23], v[26:27], v[70:71] op_sel_hi:[1,0]
	v_pk_mul_f32 v[10:11], v[10:11], v[70:71] op_sel_hi:[1,0]
	v_pk_mul_f32 v[12:13], v[12:13], v[70:71] op_sel_hi:[1,0]
	v_pk_mul_f32 v[6:7], v[6:7], v[70:71] op_sel_hi:[1,0]
	v_pk_mul_f32 v[8:9], v[8:9], v[70:71] op_sel_hi:[1,0]
	v_pk_mul_f32 v[2:3], v[2:3], v[70:71] op_sel_hi:[1,0]
	v_pk_mul_f32 v[4:5], v[4:5], v[70:71] op_sel_hi:[1,0]
	v_cmp_lt_i32_e32 vcc, s2, v38
	s_or_b64 s[12:13], vcc, s[12:13]
	s_nop 0
	v_pk_mul_f32 v[18:19], v[104:105], v[22:23]
	v_pk_mul_f32 v[22:23], v[28:29], v[70:71] op_sel_hi:[1,0]
	s_nop 0
	v_pk_mul_f32 v[20:21], v[106:107], v[22:23]
	global_store_dwordx4 v[68:69], v[18:21], off offset:1024
	s_nop 0
	v_pk_mul_f32 v[14:15], v[14:15], v[108:109]
	v_pk_mul_f32 v[16:17], v[16:17], v[110:111]
	global_store_dwordx4 v[68:69], v[14:17], off offset:2048
	s_nop 0
	v_pk_mul_f32 v[10:11], v[10:11], v[112:113]
	v_pk_mul_f32 v[12:13], v[12:13], v[114:115]
	global_store_dwordx4 v[68:69], v[10:13], off offset:3072
	s_nop 0
	v_pk_mul_f32 v[6:7], v[6:7], v[116:117]
	v_pk_mul_f32 v[8:9], v[8:9], v[118:119]
	global_store_dwordx4 v[66:67], v[6:9], off
	s_nop 0
	v_pk_mul_f32 v[2:3], v[2:3], v[120:121]
	v_pk_mul_f32 v[4:5], v[4:5], v[122:123]
	global_store_dwordx4 v[64:65], v[2:5], off
	v_pk_mul_f32 v[6:7], v[34:35], v[70:71] op_sel_hi:[1,0]
	s_nop 0
	v_pk_mul_f32 v[2:3], v[6:7], v[124:125]
	v_pk_mul_f32 v[6:7], v[36:37], v[70:71] op_sel_hi:[1,0]
	s_nop 0
	v_pk_mul_f32 v[4:5], v[6:7], v[126:127]
	global_store_dwordx4 v[62:63], v[2:5], off
	v_pk_mul_f32 v[6:7], v[30:31], v[70:71] op_sel_hi:[1,0]
	s_nop 0
	v_pk_mul_f32 v[2:3], v[6:7], v[128:129]
	v_pk_mul_f32 v[6:7], v[32:33], v[70:71] op_sel_hi:[1,0]
	s_nop 0
	v_pk_mul_f32 v[4:5], v[6:7], v[130:131]
	global_store_dwordx4 v[60:61], v[2:5], off
	s_andn2_b64 exec, exec, s[12:13]
	s_cbranch_execnz .LBB0_29
